# mLSTM chunk scans (cumulative gate sum, running max) as DPP scans on the VALU instead of 12 dependent ds_bpermute hops executed by wave 0 while the other waves wait at the chunk barrier
# baseline (speedup 1.0000x reference)
.LBB0_654:
	s_mov_b32 s1, 0xbfb8aa3b
	s_waitcnt vmcnt(2)
	v_mul_f32_e64 v66, |v137|, s1
	v_exp_f32_e32 v96, v66
	s_mov_b32 s16, 0x3e9b6dac
	v_max_f32_e32 v66, v137, v137
	v_min_f32_e32 v66, 0, v66
	v_add_f32_e32 v70, 1.0, v96
	v_add_f32_e32 v67, -1.0, v70
	v_sub_f32_e32 v68, v67, v70
	v_sub_f32_e32 v67, v96, v67
	v_add_f32_e32 v68, 1.0, v68
	v_add_f32_e32 v71, v67, v68
	s_waitcnt vmcnt(0)
	v_mul_f32_e64 v67, |v138|, s1
	v_exp_f32_e32 v97, v67
	v_cvt_f64_f32_e32 v[68:69], v70
	v_frexp_exp_i32_f64_e32 v73, v[68:69]
	s_mov_b32 s1, 0x3f2aaaab
	v_add_f32_e32 v74, 1.0, v97
	v_add_f32_e32 v68, -1.0, v74
	v_sub_f32_e32 v69, v68, v74
	v_add_f32_e32 v69, 1.0, v69
	v_sub_f32_e32 v68, v97, v68
	v_add_f32_e32 v75, v68, v69
	v_frexp_mant_f32_e32 v76, v74
	v_cvt_f64_f32_e32 v[68:69], v74
	v_frexp_exp_i32_f64_e32 v68, v[68:69]
	v_cmp_gt_f32_e32 vcc, s1, v76
	v_frexp_mant_f32_e32 v72, v70
	v_max_f32_e32 v67, v138, v138
	v_subbrev_co_u32_e32 v88, vcc, 0, v68, vcc
	v_cmp_gt_f32_e32 vcc, s1, v72
	s_mov_b32 s1, 0x7f800000
	v_min_f32_e32 v67, 0, v67
	v_subbrev_co_u32_e32 v89, vcc, 0, v73, vcc
	v_sub_u32_e32 v69, 0, v89
	v_ldexp_f32 v68, v70, v69
	v_ldexp_f32 v70, v71, v69
	v_sub_u32_e32 v71, 0, v88
	v_ldexp_f32 v69, v74, v71
	v_pk_add_f32 v[72:73], v[68:69], 1.0 op_sel_hi:[1,0]
	v_ldexp_f32 v71, v75, v71
	v_pk_add_f32 v[74:75], v[72:73], -1.0 op_sel_hi:[1,0]
	v_pk_add_f32 v[80:81], v[68:69], -1.0 op_sel_hi:[1,0]
	v_pk_add_f32 v[74:75], v[68:69], v[74:75] neg_lo:[0,1] neg_hi:[0,1]
	v_pk_add_f32 v[82:83], v[80:81], 1.0 op_sel_hi:[1,0]
	v_pk_add_f32 v[74:75], v[70:71], v[74:75]
	v_pk_add_f32 v[68:69], v[68:69], v[82:83] neg_lo:[0,1] neg_hi:[0,1]
	v_pk_add_f32 v[76:77], v[72:73], v[74:75]
	v_pk_add_f32 v[68:69], v[70:71], v[68:69]
	v_rcp_f32_e32 v78, v76
	v_rcp_f32_e32 v79, v77
	v_pk_add_f32 v[70:71], v[80:81], v[68:69]
	v_pk_add_f32 v[72:73], v[76:77], v[72:73] neg_lo:[0,1] neg_hi:[0,1]
	v_pk_add_f32 v[80:81], v[70:71], v[80:81] neg_lo:[0,1] neg_hi:[0,1]
	v_pk_add_f32 v[72:73], v[74:75], v[72:73] neg_lo:[0,1] neg_hi:[0,1]
	v_pk_mul_f32 v[74:75], v[70:71], v[78:79]
	v_pk_add_f32 v[68:69], v[68:69], v[80:81] neg_lo:[0,1] neg_hi:[0,1]
	v_pk_mul_f32 v[80:81], v[76:77], v[74:75]
	v_cmp_neq_f32_e32 vcc, s1, v96
	v_pk_fma_f32 v[82:83], v[74:75], v[76:77], v[80:81] neg_lo:[0,0,1] neg_hi:[0,0,1]
	v_readlane_b32 s18, v255, 7
	v_pk_fma_f32 v[82:83], v[74:75], v[72:73], v[82:83]
	v_readlane_b32 s19, v255, 8
	v_pk_add_f32 v[84:85], v[80:81], v[82:83]
	s_nop 0
	v_pk_add_f32 v[86:87], v[70:71], v[84:85] neg_lo:[0,1] neg_hi:[0,1]
	v_pk_add_f32 v[80:81], v[84:85], v[80:81] neg_lo:[0,1] neg_hi:[0,1]
	v_pk_add_f32 v[70:71], v[70:71], v[86:87] neg_lo:[0,1] neg_hi:[0,1]
	s_nop 0
	v_pk_add_f32 v[70:71], v[70:71], v[84:85] neg_lo:[0,1] neg_hi:[0,1]
	s_nop 0
	v_pk_add_f32 v[68:69], v[68:69], v[70:71]
	v_pk_add_f32 v[70:71], v[80:81], v[82:83] neg_lo:[0,1] neg_hi:[0,1]
	s_nop 0
	v_pk_add_f32 v[68:69], v[70:71], v[68:69]
	s_nop 0
	v_pk_add_f32 v[70:71], v[86:87], v[68:69]
	s_nop 0
	v_pk_mul_f32 v[80:81], v[78:79], v[70:71]
	s_nop 0
	v_pk_mul_f32 v[82:83], v[76:77], v[80:81]
	s_nop 0
	v_pk_fma_f32 v[76:77], v[80:81], v[76:77], v[82:83] neg_lo:[0,0,1] neg_hi:[0,0,1]
	s_nop 0
	v_pk_fma_f32 v[72:73], v[80:81], v[72:73], v[76:77]
	v_pk_add_f32 v[76:77], v[86:87], v[70:71] neg_lo:[0,1] neg_hi:[0,1]
	s_nop 0
	v_pk_add_f32 v[68:69], v[68:69], v[76:77]
	v_pk_add_f32 v[76:77], v[82:83], v[72:73]
	s_nop 0
	v_pk_add_f32 v[84:85], v[70:71], v[76:77] neg_lo:[0,1] neg_hi:[0,1]
	v_pk_add_f32 v[82:83], v[76:77], v[82:83] neg_lo:[0,1] neg_hi:[0,1]
	v_pk_add_f32 v[70:71], v[70:71], v[84:85] neg_lo:[0,1] neg_hi:[0,1]
	s_nop 0
	v_pk_add_f32 v[70:71], v[70:71], v[76:77] neg_lo:[0,1] neg_hi:[0,1]
	s_nop 0
	v_pk_add_f32 v[68:69], v[68:69], v[70:71]
	v_pk_add_f32 v[70:71], v[82:83], v[72:73] neg_lo:[0,1] neg_hi:[0,1]
	s_nop 0
	v_pk_add_f32 v[68:69], v[70:71], v[68:69]
	v_pk_add_f32 v[70:71], v[74:75], v[80:81]
	v_pk_add_f32 v[68:69], v[84:85], v[68:69]
	v_pk_add_f32 v[72:73], v[70:71], v[74:75] neg_lo:[0,1] neg_hi:[0,1]
	v_pk_mul_f32 v[68:69], v[78:79], v[68:69]
	v_pk_add_f32 v[72:73], v[80:81], v[72:73] neg_lo:[0,1] neg_hi:[0,1]
	v_cvt_f32_i32_e32 v75, v88
	v_pk_add_f32 v[68:69], v[72:73], v[68:69]
	v_cvt_f32_i32_e32 v74, v89
	v_pk_add_f32 v[72:73], v[70:71], v[68:69]
	s_nop 0
	v_pk_mul_f32 v[76:77], v[72:73], v[72:73]
	v_pk_add_f32 v[70:71], v[72:73], v[70:71] neg_lo:[0,1] neg_hi:[0,1]
	v_pk_fma_f32 v[78:79], v[76:77], s[16:17], v[170:171] op_sel_hi:[1,0,0]
	s_mov_b32 s16, 0x3f2aaada
	v_pk_add_f32 v[68:69], v[68:69], v[70:71] neg_lo:[0,1] neg_hi:[0,1]
	v_ldexp_f32 v70, v72, 1
	v_pk_fma_f32 v[78:79], v[76:77], v[78:79], s[16:17] op_sel_hi:[1,1,0]
	v_ldexp_f32 v71, v73, 1
	v_pk_mul_f32 v[72:73], v[72:73], v[76:77]
	s_mov_b32 s16, 0x3f317218
	v_pk_mul_f32 v[72:73], v[72:73], v[78:79]
	v_ldexp_f32 v85, v69, 1
	v_pk_add_f32 v[76:77], v[70:71], v[72:73]
	v_ldexp_f32 v68, v68, 1
	v_pk_add_f32 v[70:71], v[76:77], v[70:71] neg_lo:[0,1] neg_hi:[0,1]
	v_pk_mul_f32 v[80:81], v[74:75], s[16:17] op_sel_hi:[1,0]
	v_pk_add_f32 v[70:71], v[72:73], v[70:71] neg_lo:[0,1] neg_hi:[0,1]
	v_mov_b32_e32 v69, v85
	v_pk_fma_f32 v[82:83], v[74:75], s[16:17], v[80:81] op_sel_hi:[1,0,1] neg_lo:[0,0,1] neg_hi:[0,0,1]
	s_mov_b32 s16, 0xb102e308
	v_pk_add_f32 v[78:79], v[68:69], v[70:71]
	v_pk_fma_f32 v[74:75], v[74:75], s[16:17], v[82:83] op_sel_hi:[1,0,1]
	v_mov_b32_e32 v73, v71
	v_mov_b32_e32 v69, v79
	v_mov_b32_e32 v71, v77
	v_pk_add_f32 v[82:83], v[80:81], v[74:75]
	v_mov_b32_e32 v72, v80
	v_mov_b32_e32 v84, v74
	v_pk_add_f32 v[68:69], v[68:69], v[70:71]
	v_pk_add_f32 v[70:71], v[76:77], v[78:79]
	v_pk_add_f32 v[72:73], v[72:73], v[84:85]
	v_mov_b32_e32 v84, v82
	v_mov_b32_e32 v85, v81
	v_mov_b32_e32 v86, v70
	v_mov_b32_e32 v87, v75
	v_mov_b32_e32 v90, v82
	v_mov_b32_e32 v91, v77
	v_mov_b32_e32 v92, v70
	v_mov_b32_e32 v93, v79
	v_pk_add_f32 v[88:89], v[84:85], v[86:87]
	v_pk_add_f32 v[90:91], v[90:91], v[92:93]
	v_pk_add_f32 v[92:93], v[82:83], v[70:71]
	v_pk_add_f32 v[84:85], v[88:89], v[84:85] neg_lo:[0,1] neg_hi:[0,1]
	v_mov_b32_e32 v88, v70
	v_mov_b32_e32 v89, v93
	v_mov_b32_e32 v94, v76
	v_mov_b32_e32 v95, v83
	v_pk_add_f32 v[88:89], v[88:89], v[94:95] neg_lo:[0,1] neg_hi:[0,1]
	v_mov_b32_e32 v94, v82
	v_mov_b32_e32 v95, v93
	v_mov_b32_e32 v81, v89
	v_pk_add_f32 v[80:81], v[94:95], v[80:81] neg_lo:[0,1] neg_hi:[0,1]
	v_pk_add_f32 v[86:87], v[86:87], v[84:85] neg_lo:[0,1] neg_hi:[0,1]
	v_mov_b32_e32 v94, v80
	v_mov_b32_e32 v95, v85
	v_mov_b32_e32 v85, v77
	v_pk_add_f32 v[94:95], v[74:75], v[94:95] neg_lo:[0,1] neg_hi:[0,1]
	v_pk_add_f32 v[84:85], v[90:91], v[84:85] neg_lo:[0,1] neg_hi:[0,1]
	v_mov_b32_e32 v75, v83
	v_pk_add_f32 v[72:73], v[72:73], v[84:85] neg_lo:[0,1] neg_hi:[0,1]
	v_pk_add_f32 v[74:75], v[74:75], v[80:81] neg_lo:[0,1] neg_hi:[0,1]
	v_pk_add_f32 v[68:69], v[68:69], v[88:89] neg_lo:[0,1] neg_hi:[0,1]
	v_pk_add_f32 v[70:71], v[70:71], v[76:77] neg_lo:[0,1] neg_hi:[0,1]
	v_pk_add_f32 v[76:77], v[68:69], v[74:75]
	v_mov_b32_e32 v69, v73
	v_pk_add_f32 v[70:71], v[78:79], v[70:71] neg_lo:[0,1] neg_hi:[0,1]
	v_pk_add_f32 v[78:79], v[86:87], v[72:73]
	v_pk_add_f32 v[68:69], v[94:95], v[68:69]
	v_mov_b32_e32 v75, v87
	v_pk_add_f32 v[68:69], v[68:69], v[74:75] neg_lo:[0,1] neg_hi:[0,1]
	v_mov_b32_e32 v72, v76
	v_mov_b32_e32 v73, v79
	v_pk_add_f32 v[72:73], v[72:73], v[68:69] neg_lo:[0,1] neg_hi:[0,1]
	v_pk_add_f32 v[68:69], v[70:71], v[68:69] neg_lo:[0,1] neg_hi:[0,1]
	v_pk_add_f32 v[72:73], v[74:75], v[72:73] neg_lo:[0,1] neg_hi:[0,1]
	v_pk_add_f32 v[70:71], v[78:79], v[76:77]
	v_pk_add_f32 v[68:69], v[68:69], v[72:73]
	v_pk_add_f32 v[72:73], v[92:93], v[70:71]
	v_readlane_b32 s16, v254, 62
	v_pk_add_f32 v[74:75], v[72:73], v[92:93] neg_lo:[0,1] neg_hi:[0,1]
	v_readlane_b32 s17, v254, 63
	v_pk_add_f32 v[70:71], v[70:71], v[74:75] neg_lo:[0,1] neg_hi:[0,1]
	s_nop 0
	v_pk_add_f32 v[68:69], v[68:69], v[70:71]
	s_nop 0
	v_pk_add_f32 v[68:69], v[72:73], v[68:69]
	s_nop 0
	v_cndmask_b32_e32 v68, v218, v68, vcc
	v_cmp_neq_f32_e32 vcc, s1, v97
	s_mov_b32 s1, 0x33800000
	s_nop 0
	v_cndmask_b32_e32 v69, v218, v69, vcc
	v_cmp_ngt_f32_e32 vcc, -1.0, v97
	s_nop 1
	v_cndmask_b32_e32 v69, v219, v69, vcc
	v_cmp_ngt_f32_e32 vcc, -1.0, v96
	s_nop 1
	v_cndmask_b32_e32 v68, v219, v68, vcc
	v_cmp_neq_f32_e32 vcc, -1.0, v96
	s_nop 1
	v_cndmask_b32_e32 v68, v168, v68, vcc
	v_cmp_neq_f32_e32 vcc, -1.0, v97
	s_nop 1
	v_cndmask_b32_e32 v69, v168, v69, vcc
	v_cmp_lt_f32_e64 vcc, |v97|, s1
	s_nop 1
	v_cndmask_b32_e32 v69, v69, v97, vcc
	v_cmp_lt_f32_e64 vcc, |v96|, s1
	s_nop 1
	v_cndmask_b32_e32 v68, v68, v96, vcc
	v_pk_add_f32 v[66:67], v[66:67], v[68:69] neg_lo:[0,1] neg_hi:[0,1]
	v_readlane_b32 vcc_lo, v255, 5
	v_pk_add_f32 v[68:69], v[66:67], v[66:67] op_sel:[0,1] op_sel_hi:[1,0]
	v_mov_b32_e32 v67, v68
	s_nop 1
	v_add_f32_dpp v67, v67, v67 row_shr:1 row_mask:0xf bank_mask:0xf
	s_nop 1
	v_add_f32_dpp v67, v67, v67 row_shr:2 row_mask:0xf bank_mask:0xf
	s_nop 1
	v_add_f32_dpp v67, v67, v67 row_shr:4 row_mask:0xf bank_mask:0xf
	s_nop 1
	v_add_f32_dpp v67, v67, v67 row_shr:8 row_mask:0xf bank_mask:0xf
	s_nop 1
	v_add_f32_dpp v67, v67, v67 row_bcast:15 row_mask:0xa bank_mask:0xf
	s_nop 1
	v_add_f32_dpp v67, v67, v67 row_bcast:31 row_mask:0xc bank_mask:0xf
	v_readlane_b32 vcc_hi, v255, 6
	v_sub_f32_e32 v67, v67, v68
	v_pk_mov_b32 v[68:69], v[66:67], v[68:69] op_sel:[1,0]
	s_nop 0
	v_pk_add_f32 v[66:67], v[66:67], v[68:69]
	s_nop 0
	v_pk_add_f32 v[68:69], v[108:109], v[66:67] neg_lo:[0,1] neg_hi:[0,1]
	s_nop 0
	v_max_f32_e32 v70, v68, v69
	s_nop 1
	v_max_f32_dpp v70, v70, v70 row_shr:1 row_mask:0xf bank_mask:0xf
	s_nop 1
	v_max_f32_dpp v70, v70, v70 row_shr:2 row_mask:0xf bank_mask:0xf
	s_nop 1
	v_max_f32_dpp v70, v70, v70 row_shr:4 row_mask:0xf bank_mask:0xf
	s_nop 1
	v_max_f32_dpp v70, v70, v70 row_shr:8 row_mask:0xf bank_mask:0xf
	s_nop 1
	v_max_f32_dpp v70, v70, v70 row_bcast:15 row_mask:0xa bank_mask:0xf
	s_nop 1
	v_max_f32_dpp v70, v70, v70 row_bcast:31 row_mask:0xc bank_mask:0xf
	ds_bpermute_b32 v71, v146, v70
	v_add_u32_e32 v72, 0, v103
	v_add_u32_e32 v73, 0x22000, v72
	ds_write_b64 v73, v[66:67]
	v_add_u32_e32 v67, 0x22200, v72
	s_waitcnt lgkmcnt(1)
	v_cndmask_b32_e64 v66, v71, v168, s[12:13]
	ds_write_b64 v67, v[68:69]
	v_max_f32_e32 v67, v70, v70
	v_max_f32_e32 v69, v181, v181
	v_max3_f32 v66, v181, v66, v68
	v_add_u32_e32 v68, 0x22400, v72
	v_max_f32_e32 v67, v69, v67
	ds_write_b64 v68, v[66:67]

.LBB0_681:
	s_and_saveexec_b64 s[96:97], s[10:11]
	s_cbranch_execz .LBB0_683
	s_mov_b32 s2, 0xbfb8aa3b
	s_waitcnt vmcnt(2)
	v_mul_f32_e64 v66, |v123|, s2
	v_exp_f32_e32 v96, v66
	v_max_f32_e32 v66, v123, v123
	v_min_f32_e32 v66, 0, v66
	v_add_f32_e32 v70, 1.0, v96
	v_add_f32_e32 v67, -1.0, v70
	v_sub_f32_e32 v68, v67, v70
	v_sub_f32_e32 v67, v96, v67
	v_add_f32_e32 v68, 1.0, v68
	v_add_f32_e32 v71, v67, v68
	s_waitcnt vmcnt(0)
	v_mul_f32_e64 v67, |v124|, s2
	v_exp_f32_e32 v97, v67
	v_cvt_f64_f32_e32 v[68:69], v70
	v_frexp_exp_i32_f64_e32 v73, v[68:69]
	s_mov_b32 s2, 0x3f2aaaab
	v_add_f32_e32 v74, 1.0, v97
	v_add_f32_e32 v68, -1.0, v74
	v_sub_f32_e32 v69, v68, v74
	v_add_f32_e32 v69, 1.0, v69
	v_sub_f32_e32 v68, v97, v68
	v_add_f32_e32 v75, v68, v69
	v_frexp_mant_f32_e32 v76, v74
	v_cvt_f64_f32_e32 v[68:69], v74
	v_frexp_exp_i32_f64_e32 v68, v[68:69]
	v_cmp_gt_f32_e32 vcc, s2, v76
	v_frexp_mant_f32_e32 v72, v70
	v_max_f32_e32 v67, v124, v124
	v_subbrev_co_u32_e32 v88, vcc, 0, v68, vcc
	v_cmp_gt_f32_e32 vcc, s2, v72
	s_mov_b32 s2, 0x3e9b6dac
	v_min_f32_e32 v67, 0, v67
	v_subbrev_co_u32_e32 v89, vcc, 0, v73, vcc
	v_sub_u32_e32 v69, 0, v89
	v_ldexp_f32 v68, v70, v69
	v_ldexp_f32 v70, v71, v69
	v_sub_u32_e32 v71, 0, v88
	v_ldexp_f32 v69, v74, v71
	v_pk_add_f32 v[72:73], v[68:69], 1.0 op_sel_hi:[1,0]
	v_ldexp_f32 v71, v75, v71
	v_pk_add_f32 v[74:75], v[72:73], -1.0 op_sel_hi:[1,0]
	v_pk_add_f32 v[80:81], v[68:69], -1.0 op_sel_hi:[1,0]
	v_pk_add_f32 v[74:75], v[68:69], v[74:75] neg_lo:[0,1] neg_hi:[0,1]
	v_pk_add_f32 v[82:83], v[80:81], 1.0 op_sel_hi:[1,0]
	v_pk_add_f32 v[74:75], v[70:71], v[74:75]
	v_pk_add_f32 v[68:69], v[68:69], v[82:83] neg_lo:[0,1] neg_hi:[0,1]
	v_pk_add_f32 v[76:77], v[72:73], v[74:75]
	v_pk_add_f32 v[68:69], v[70:71], v[68:69]
	v_rcp_f32_e32 v78, v76
	v_rcp_f32_e32 v79, v77
	v_pk_add_f32 v[70:71], v[80:81], v[68:69]
	v_pk_add_f32 v[72:73], v[76:77], v[72:73] neg_lo:[0,1] neg_hi:[0,1]
	v_pk_add_f32 v[80:81], v[70:71], v[80:81] neg_lo:[0,1] neg_hi:[0,1]
	v_pk_add_f32 v[72:73], v[74:75], v[72:73] neg_lo:[0,1] neg_hi:[0,1]
	v_pk_mul_f32 v[74:75], v[70:71], v[78:79]
	v_pk_add_f32 v[68:69], v[68:69], v[80:81] neg_lo:[0,1] neg_hi:[0,1]
	v_pk_mul_f32 v[80:81], v[76:77], v[74:75]
	s_nop 0
	v_pk_fma_f32 v[82:83], v[74:75], v[76:77], v[80:81] neg_lo:[0,0,1] neg_hi:[0,0,1]
	s_nop 0
	v_pk_fma_f32 v[82:83], v[74:75], v[72:73], v[82:83]
	s_nop 0
	v_pk_add_f32 v[84:85], v[80:81], v[82:83]
	s_nop 0
	v_pk_add_f32 v[86:87], v[70:71], v[84:85] neg_lo:[0,1] neg_hi:[0,1]
	v_pk_add_f32 v[80:81], v[84:85], v[80:81] neg_lo:[0,1] neg_hi:[0,1]
	v_pk_add_f32 v[70:71], v[70:71], v[86:87] neg_lo:[0,1] neg_hi:[0,1]
	s_nop 0
	v_pk_add_f32 v[70:71], v[70:71], v[84:85] neg_lo:[0,1] neg_hi:[0,1]
	s_nop 0
	v_pk_add_f32 v[68:69], v[68:69], v[70:71]
	v_pk_add_f32 v[70:71], v[80:81], v[82:83] neg_lo:[0,1] neg_hi:[0,1]
	s_nop 0
	v_pk_add_f32 v[68:69], v[70:71], v[68:69]
	s_nop 0
	v_pk_add_f32 v[70:71], v[86:87], v[68:69]
	s_nop 0
	v_pk_mul_f32 v[80:81], v[78:79], v[70:71]
	s_nop 0
	v_pk_mul_f32 v[82:83], v[76:77], v[80:81]
	s_nop 0
	v_pk_fma_f32 v[76:77], v[80:81], v[76:77], v[82:83] neg_lo:[0,0,1] neg_hi:[0,0,1]
	s_nop 0
	v_pk_fma_f32 v[72:73], v[80:81], v[72:73], v[76:77]
	v_pk_add_f32 v[76:77], v[86:87], v[70:71] neg_lo:[0,1] neg_hi:[0,1]
	s_nop 0
	v_pk_add_f32 v[68:69], v[68:69], v[76:77]
	v_pk_add_f32 v[76:77], v[82:83], v[72:73]
	s_nop 0
	v_pk_add_f32 v[84:85], v[70:71], v[76:77] neg_lo:[0,1] neg_hi:[0,1]
	v_pk_add_f32 v[82:83], v[76:77], v[82:83] neg_lo:[0,1] neg_hi:[0,1]
	v_pk_add_f32 v[70:71], v[70:71], v[84:85] neg_lo:[0,1] neg_hi:[0,1]
	s_nop 0
	v_pk_add_f32 v[70:71], v[70:71], v[76:77] neg_lo:[0,1] neg_hi:[0,1]
	s_nop 0
	v_pk_add_f32 v[68:69], v[68:69], v[70:71]
	v_pk_add_f32 v[70:71], v[82:83], v[72:73] neg_lo:[0,1] neg_hi:[0,1]
	s_nop 0
	v_pk_add_f32 v[68:69], v[70:71], v[68:69]
	v_pk_add_f32 v[70:71], v[74:75], v[80:81]
	v_pk_add_f32 v[68:69], v[84:85], v[68:69]
	v_pk_add_f32 v[72:73], v[70:71], v[74:75] neg_lo:[0,1] neg_hi:[0,1]
	v_pk_mul_f32 v[68:69], v[78:79], v[68:69]
	v_pk_add_f32 v[72:73], v[80:81], v[72:73] neg_lo:[0,1] neg_hi:[0,1]
	v_cvt_f32_i32_e32 v75, v88
	v_pk_add_f32 v[68:69], v[72:73], v[68:69]
	v_cvt_f32_i32_e32 v74, v89
	v_pk_add_f32 v[72:73], v[70:71], v[68:69]
	s_nop 0
	v_pk_mul_f32 v[76:77], v[72:73], v[72:73]
	v_pk_add_f32 v[70:71], v[72:73], v[70:71] neg_lo:[0,1] neg_hi:[0,1]
	v_pk_fma_f32 v[78:79], v[76:77], s[2:3], v[170:171] op_sel_hi:[1,0,0]
	s_mov_b32 s2, 0x3f2aaada
	v_pk_add_f32 v[68:69], v[68:69], v[70:71] neg_lo:[0,1] neg_hi:[0,1]
	v_ldexp_f32 v70, v72, 1
	v_pk_fma_f32 v[78:79], v[76:77], v[78:79], s[2:3] op_sel_hi:[1,1,0]
	v_ldexp_f32 v71, v73, 1
	v_pk_mul_f32 v[72:73], v[72:73], v[76:77]
	s_mov_b32 s2, 0x3f317218
	v_pk_mul_f32 v[72:73], v[72:73], v[78:79]
	v_ldexp_f32 v85, v69, 1
	v_pk_add_f32 v[76:77], v[70:71], v[72:73]
	v_ldexp_f32 v68, v68, 1
	v_pk_add_f32 v[70:71], v[76:77], v[70:71] neg_lo:[0,1] neg_hi:[0,1]
	v_pk_mul_f32 v[80:81], v[74:75], s[2:3] op_sel_hi:[1,0]
	v_pk_add_f32 v[70:71], v[72:73], v[70:71] neg_lo:[0,1] neg_hi:[0,1]
	v_mov_b32_e32 v69, v85
	v_pk_fma_f32 v[82:83], v[74:75], s[2:3], v[80:81] op_sel_hi:[1,0,1] neg_lo:[0,0,1] neg_hi:[0,0,1]
	s_mov_b32 s2, 0xb102e308
	v_pk_add_f32 v[78:79], v[68:69], v[70:71]
	v_pk_fma_f32 v[74:75], v[74:75], s[2:3], v[82:83] op_sel_hi:[1,0,1]
	v_mov_b32_e32 v73, v71
	v_mov_b32_e32 v69, v79
	v_mov_b32_e32 v71, v77
	v_pk_add_f32 v[82:83], v[80:81], v[74:75]
	v_mov_b32_e32 v72, v80
	v_mov_b32_e32 v84, v74
	v_pk_add_f32 v[68:69], v[68:69], v[70:71]
	v_pk_add_f32 v[70:71], v[76:77], v[78:79]
	v_pk_add_f32 v[72:73], v[72:73], v[84:85]
	v_mov_b32_e32 v84, v82
	v_mov_b32_e32 v85, v81
	v_mov_b32_e32 v86, v70
	v_mov_b32_e32 v87, v75
	v_mov_b32_e32 v90, v82
	v_mov_b32_e32 v91, v77
	v_mov_b32_e32 v92, v70
	v_mov_b32_e32 v93, v79
	v_pk_add_f32 v[88:89], v[84:85], v[86:87]
	v_pk_add_f32 v[90:91], v[90:91], v[92:93]
	v_pk_add_f32 v[92:93], v[82:83], v[70:71]
	v_pk_add_f32 v[84:85], v[88:89], v[84:85] neg_lo:[0,1] neg_hi:[0,1]
	v_mov_b32_e32 v88, v70
	v_mov_b32_e32 v89, v93
	v_mov_b32_e32 v94, v76
	v_mov_b32_e32 v95, v83
	v_pk_add_f32 v[88:89], v[88:89], v[94:95] neg_lo:[0,1] neg_hi:[0,1]
	v_mov_b32_e32 v94, v82
	v_mov_b32_e32 v95, v93
	v_mov_b32_e32 v81, v89
	v_pk_add_f32 v[80:81], v[94:95], v[80:81] neg_lo:[0,1] neg_hi:[0,1]
	v_pk_add_f32 v[86:87], v[86:87], v[84:85] neg_lo:[0,1] neg_hi:[0,1]
	v_mov_b32_e32 v94, v80
	v_mov_b32_e32 v95, v85
	v_mov_b32_e32 v85, v77
	v_pk_add_f32 v[94:95], v[74:75], v[94:95] neg_lo:[0,1] neg_hi:[0,1]
	v_pk_add_f32 v[84:85], v[90:91], v[84:85] neg_lo:[0,1] neg_hi:[0,1]
	v_mov_b32_e32 v75, v83
	v_pk_add_f32 v[72:73], v[72:73], v[84:85] neg_lo:[0,1] neg_hi:[0,1]
	v_pk_add_f32 v[74:75], v[74:75], v[80:81] neg_lo:[0,1] neg_hi:[0,1]
	v_pk_add_f32 v[68:69], v[68:69], v[88:89] neg_lo:[0,1] neg_hi:[0,1]
	v_pk_add_f32 v[70:71], v[70:71], v[76:77] neg_lo:[0,1] neg_hi:[0,1]
	v_pk_add_f32 v[76:77], v[68:69], v[74:75]
	v_mov_b32_e32 v69, v73
	v_pk_add_f32 v[70:71], v[78:79], v[70:71] neg_lo:[0,1] neg_hi:[0,1]
	v_pk_add_f32 v[78:79], v[86:87], v[72:73]
	v_pk_add_f32 v[68:69], v[94:95], v[68:69]
	v_mov_b32_e32 v75, v87
	v_pk_add_f32 v[68:69], v[68:69], v[74:75] neg_lo:[0,1] neg_hi:[0,1]
	v_mov_b32_e32 v72, v76
	v_mov_b32_e32 v73, v79
	v_pk_add_f32 v[72:73], v[72:73], v[68:69] neg_lo:[0,1] neg_hi:[0,1]
	v_pk_add_f32 v[68:69], v[70:71], v[68:69] neg_lo:[0,1] neg_hi:[0,1]
	v_pk_add_f32 v[72:73], v[74:75], v[72:73] neg_lo:[0,1] neg_hi:[0,1]
	v_pk_add_f32 v[70:71], v[78:79], v[76:77]
	v_pk_add_f32 v[68:69], v[68:69], v[72:73]
	v_pk_add_f32 v[72:73], v[92:93], v[70:71]
	s_mov_b32 s2, 0x7f800000
	v_pk_add_f32 v[74:75], v[72:73], v[92:93] neg_lo:[0,1] neg_hi:[0,1]
	v_cmp_neq_f32_e32 vcc, s2, v96
	v_pk_add_f32 v[70:71], v[70:71], v[74:75] neg_lo:[0,1] neg_hi:[0,1]
	s_nop 0
	v_pk_add_f32 v[68:69], v[68:69], v[70:71]
	s_nop 0
	v_pk_add_f32 v[68:69], v[72:73], v[68:69]
	s_nop 0
	v_cndmask_b32_e32 v68, v218, v68, vcc
	v_cmp_neq_f32_e32 vcc, s2, v97
	s_mov_b32 s2, 0x33800000
	s_nop 0
	v_cndmask_b32_e32 v69, v218, v69, vcc
	v_cmp_ngt_f32_e32 vcc, -1.0, v97
	s_nop 1
	v_cndmask_b32_e32 v69, v219, v69, vcc
	v_cmp_ngt_f32_e32 vcc, -1.0, v96
	s_nop 1
	v_cndmask_b32_e32 v68, v219, v68, vcc
	v_cmp_neq_f32_e32 vcc, -1.0, v96
	s_nop 1
	v_cndmask_b32_e32 v68, v168, v68, vcc
	v_cmp_neq_f32_e32 vcc, -1.0, v97
	s_nop 1
	v_cndmask_b32_e32 v69, v168, v69, vcc
	v_cmp_lt_f32_e64 vcc, |v97|, s2
	s_nop 1
	v_cndmask_b32_e32 v69, v69, v97, vcc
	v_cmp_lt_f32_e64 vcc, |v96|, s2
	s_nop 1
	v_cndmask_b32_e32 v68, v68, v96, vcc
	v_pk_add_f32 v[66:67], v[66:67], v[68:69] neg_lo:[0,1] neg_hi:[0,1]
	s_nop 0
	v_pk_add_f32 v[68:69], v[66:67], v[66:67] op_sel:[0,1] op_sel_hi:[1,0]
	v_mov_b32_e32 v67, v68
	s_nop 1
	v_add_f32_dpp v67, v67, v67 row_shr:1 row_mask:0xf bank_mask:0xf
	s_nop 1
	v_add_f32_dpp v67, v67, v67 row_shr:2 row_mask:0xf bank_mask:0xf
	s_nop 1
	v_add_f32_dpp v67, v67, v67 row_shr:4 row_mask:0xf bank_mask:0xf
	s_nop 1
	v_add_f32_dpp v67, v67, v67 row_shr:8 row_mask:0xf bank_mask:0xf
	s_nop 1
	v_add_f32_dpp v67, v67, v67 row_bcast:15 row_mask:0xa bank_mask:0xf
	s_nop 1
	v_add_f32_dpp v67, v67, v67 row_bcast:31 row_mask:0xc bank_mask:0xf
	v_sub_f32_e32 v67, v67, v68
	v_pk_mov_b32 v[68:69], v[66:67], v[68:69] op_sel:[1,0]
	s_nop 0
	v_pk_add_f32 v[66:67], v[66:67], v[68:69]
	s_nop 0
	v_pk_add_f32 v[68:69], v[102:103], v[66:67] neg_lo:[0,1] neg_hi:[0,1]
	s_nop 0
	v_max_f32_e32 v70, v68, v69
	s_nop 1
	v_max_f32_dpp v70, v70, v70 row_shr:1 row_mask:0xf bank_mask:0xf
	s_nop 1
	v_max_f32_dpp v70, v70, v70 row_shr:2 row_mask:0xf bank_mask:0xf
	s_nop 1
	v_max_f32_dpp v70, v70, v70 row_shr:4 row_mask:0xf bank_mask:0xf
	s_nop 1
	v_max_f32_dpp v70, v70, v70 row_shr:8 row_mask:0xf bank_mask:0xf
	s_nop 1
	v_max_f32_dpp v70, v70, v70 row_bcast:15 row_mask:0xa bank_mask:0xf
	s_nop 1
	v_max_f32_dpp v70, v70, v70 row_bcast:31 row_mask:0xc bank_mask:0xf
	ds_bpermute_b32 v71, v132, v70
	v_add_u32_e32 v72, 0, v115
	v_add_u32_e32 v73, 0x22000, v72
	ds_write_b64 v73, v[66:67]
	v_add_u32_e32 v67, 0x22200, v72
	s_waitcnt lgkmcnt(1)
	v_cndmask_b32_e64 v66, v71, v168, s[12:13]
	ds_write_b64 v67, v[68:69]
	v_max_f32_e32 v67, v70, v70
	v_max_f32_e32 v69, v154, v154
	v_max3_f32 v66, v154, v66, v68
	v_add_u32_e32 v68, 0x22400, v72
	v_max_f32_e32 v67, v69, v67
	ds_write_b64 v68, v[66:67]
